# v77 + P1 tail: rope tables parked in the reducing wave's unused LDS partial-sum slot during the MFMA section, freeing 16 VGPR tuples so all fragment loads issue up front (10 -> 2 serialized waits)
# baseline (speedup 1.0000x reference)
; template <class Epi, int K>
; __device__ __forceinline__ void gemm_tail(LAS unsigned char* lds, const bf16_t* A, const bf16_t* Bt, const int N, const Epi& E, const int bid, const int G, const int tid_in) {
;     ...
;         const bf16_t* ap = A + (size_t)(MMAIN + i16) * K + wid * kw + 8 * kq;
;         const bf16_t* bp = Bt + (size_t)(256 * pn + 32 * wc + 8 * (i16 >> 2) + (i16 & 3)) * K + wid * kw + 8 * kq;
;         f32x4 acc[2][4][2];
; #pragma unroll
;         for (int bj = 0; bj < 2; ++bj)
; #pragma unroll
;             for (int m = 0; m < 4; ++m)
; #pragma unroll
;                 for (int n = 0; n < 2; ++n) acc[bj][m][n] = (f32x4){0.f, 0.f, 0.f, 0.f};
; #pragma unroll
;         for (int sb = 0; sb < NS; sb += 4) {
;             bf16x8 af[4][4], bf[4][2][2];
; #pragma unroll
;             for (int s = 0; s < 4; ++s) if (sb + s < NS) {
; #pragma unroll
;                 for (int m = 0; m < 4; ++m) af[s][m] = *(const bf16x8*)(ap + (size_t)(16 * m) * K + 32 * (sb + s));
; #pragma unroll
;                 for (int bj = 0; bj < 2; ++bj)
; #pragma unroll
;                     for (int n = 0; n < 2; ++n) bf[s][bj][n] = *(const bf16x8*)(bp + (size_t)(128 * bj + 4 * n) * K + 32 * (sb + s));
;             }
; #pragma unroll
;             for (int s = 0; s < 4; ++s) if (sb + s < NS) {
; #pragma unroll
;                 for (int bj = 0; bj < 2; ++bj)
; #pragma unroll
;                     for (int m = 0; m < 4; ++m)
; #pragma unroll
;                         for (int n = 0; n < 2; ++n) acc[bj][m][n] = __builtin_amdgcn_mfma_f32_16x16x32_bf16(bf[s][bj][n], af[s][m], acc[bj][m][n], 0, 0, 0);
;             }
.LBB0_322:
	v_add_u32_e32 v248, s2, v210
	ds_write_b128 v248, v[88:91]
	ds_write_b128 v248, v[92:95] offset:1024
	ds_write_b128 v248, v[96:99] offset:2048
	ds_write_b128 v248, v[100:103] offset:3072
	ds_write_b128 v248, v[104:107] offset:4096
	ds_write_b128 v248, v[108:111] offset:5120
	ds_write_b128 v248, v[112:115] offset:6144
	ds_write_b128 v248, v[116:119] offset:7168
	ds_write_b128 v248, v[120:123] offset:8192
	ds_write_b128 v248, v[124:127] offset:9216
	ds_write_b128 v248, v[128:131] offset:10240
	ds_write_b128 v248, v[132:135] offset:11264
	ds_write_b128 v248, v[136:139] offset:12288
	ds_write_b128 v248, v[140:143] offset:13312
	ds_write_b128 v248, v[144:147] offset:14336
	ds_write_b128 v248, v[148:151] offset:15360
	s_ashr_i32 s6, s3, 2
	s_and_b32 s27, s3, 3
	s_lshl_b32 s10, s6, 8
	v_lshl_or_b32 v0, s27, 5, v193
	v_or_b32_e32 v2, s10, v0
	v_ashrrev_i32_e32 v3, 31, v2
	v_lshlrev_b64 v[2:3], 11, v[2:3]
	v_lshl_add_u64 v[2:3], v[86:87], 0, v[2:3]
	v_add_co_u32_e32 v4, vcc, s76, v2
	global_load_dwordx4 v[6:9], v[2:3], off
	global_load_dwordx4 v[14:17], v[84:85], off
	global_load_dwordx4 v[18:21], v[152:153], off
	v_addc_co_u32_e32 v5, vcc, 0, v3, vcc
	v_add_co_u32_e32 v12, vcc, s78, v2
	global_load_dwordx4 v[42:45], v[4:5], off
	global_load_dwordx4 v[78:81], v[2:3], off offset:64
	v_addc_co_u32_e32 v13, vcc, 0, v3, vcc
	v_add_co_u32_e32 v10, vcc, s79, v2
	global_load_dwordx4 v[58:61], v[12:13], off
	s_nop 0
	v_addc_co_u32_e32 v11, vcc, 0, v3, vcc
	global_load_dwordx4 v[66:69], v[10:11], off
	global_load_dwordx4 v[26:29], v[154:155], off
	global_load_dwordx4 v[34:37], v[156:157], off
	global_load_dwordx4 v[202:205], v[160:161], off
	global_load_dwordx4 v[224:227], v[162:163], off
	global_load_dwordx4 v[198:201], v[158:159], off
	global_load_dwordx4 v[244:247], v[10:11], off offset:64
	global_load_dwordx4 v[248:251], v[172:173], off
	global_load_dwordx4 v[240:243], v[84:85], off offset:64
	global_load_dwordx4 v[88:91], v[4:5], off offset:64
	global_load_dwordx4 v[92:95], v[12:13], off offset:64
	global_load_dwordx4 v[96:99], v[4:5], off offset:128
	global_load_dwordx4 v[100:103], v[2:3], off offset:128
	global_load_dwordx4 v[104:107], v[84:85], off offset:128
	global_load_dwordx4 v[108:111], v[166:167], off
	global_load_dwordx4 v[112:115], v[164:165], off
	global_load_dwordx4 v[116:119], v[168:169], off
	global_load_dwordx4 v[120:123], v[12:13], off offset:128
	global_load_dwordx4 v[124:127], v[10:11], off offset:128
	global_load_dwordx4 v[128:131], v[2:3], off offset:192
	global_load_dwordx4 v[132:135], v[84:85], off offset:192
	global_load_dwordx4 v[136:139], v[4:5], off offset:192
	global_load_dwordx4 v[140:143], v[170:171], off
	global_load_dwordx4 v[144:147], v[174:175], off
	global_load_dwordx4 v[148:151], v[12:13], off offset:192
	s_waitcnt vmcnt(29)
	v_mfma_f32_16x16x32_bf16 v[22:25], v[6:9], v[14:17], 0
	s_waitcnt vmcnt(28)
	v_mfma_f32_16x16x32_bf16 v[30:33], v[6:9], v[18:21], 0
	s_waitcnt vmcnt(23)
	v_mfma_f32_16x16x32_bf16 v[38:41], v[6:9], v[26:29], 0
	s_waitcnt vmcnt(22)
	v_mfma_f32_16x16x32_bf16 v[6:9], v[6:9], v[34:37], 0
	v_mfma_f32_16x16x32_bf16 v[46:49], v[42:45], v[14:17], 0
	v_mfma_f32_16x16x32_bf16 v[50:53], v[42:45], v[18:21], 0
	v_mfma_f32_16x16x32_bf16 v[54:57], v[42:45], v[26:29], 0
	v_mfma_f32_16x16x32_bf16 v[42:45], v[42:45], v[34:37], 0
	v_mfma_f32_16x16x32_bf16 v[62:65], v[58:61], v[14:17], 0
	v_mfma_f32_16x16x32_bf16 v[14:17], v[66:69], v[14:17], 0
	v_mfma_f32_16x16x32_bf16 v[70:73], v[58:61], v[18:21], 0
	v_mfma_f32_16x16x32_bf16 v[18:21], v[66:69], v[18:21], 0
	v_mfma_f32_16x16x32_bf16 v[74:77], v[58:61], v[26:29], 0
	v_mfma_f32_16x16x32_bf16 v[26:29], v[66:69], v[26:29], 0
	v_mfma_f32_16x16x32_bf16 v[58:61], v[58:61], v[34:37], 0
	v_mfma_f32_16x16x32_bf16 v[34:37], v[66:69], v[34:37], 0
	s_waitcnt vmcnt(16)
	v_mfma_f32_16x16x32_bf16 v[22:25], v[78:81], v[240:243], v[22:25]
	v_mfma_f32_16x16x32_bf16 v[30:33], v[78:81], v[198:201], v[30:33]
	v_mfma_f32_16x16x32_bf16 v[38:41], v[78:81], v[202:205], v[38:41]
	v_mfma_f32_16x16x32_bf16 v[6:9], v[78:81], v[224:227], v[6:9]
	s_waitcnt vmcnt(15)
	v_mfma_f32_16x16x32_bf16 v[46:49], v[88:91], v[240:243], v[46:49]
	v_mfma_f32_16x16x32_bf16 v[50:53], v[88:91], v[198:201], v[50:53]
	v_mfma_f32_16x16x32_bf16 v[54:57], v[88:91], v[202:205], v[54:57]
	v_mfma_f32_16x16x32_bf16 v[42:45], v[88:91], v[224:227], v[42:45]
	s_waitcnt vmcnt(14)
	v_mfma_f32_16x16x32_bf16 v[62:65], v[92:95], v[240:243], v[62:65]
	v_mfma_f32_16x16x32_bf16 v[14:17], v[244:247], v[240:243], v[14:17]
	v_mfma_f32_16x16x32_bf16 v[66:69], v[92:95], v[198:201], v[70:73]
	v_mfma_f32_16x16x32_bf16 v[18:21], v[244:247], v[198:201], v[18:21]
	v_mfma_f32_16x16x32_bf16 v[70:73], v[92:95], v[202:205], v[74:77]
	s_nop 2
	v_mfma_f32_16x16x32_bf16 v[58:61], v[92:95], v[224:227], v[58:61]
	v_mfma_f32_16x16x32_bf16 v[34:37], v[244:247], v[224:227], v[34:37]
	v_mfma_f32_16x16x32_bf16 v[26:29], v[244:247], v[202:205], v[26:29]
	s_waitcnt vmcnt(10)
	v_mfma_f32_16x16x32_bf16 v[228:231], v[96:99], v[108:111], v[54:57]
	s_nop 2
	v_mfma_f32_16x16x32_bf16 v[22:25], v[100:103], v[104:107], v[22:25]
	v_mfma_f32_16x16x32_bf16 v[46:49], v[96:99], v[104:107], v[46:49]
	s_waitcnt vmcnt(9)
	v_mfma_f32_16x16x32_bf16 v[30:33], v[100:103], v[112:115], v[30:33]
	v_mfma_f32_16x16x32_bf16 v[50:53], v[96:99], v[112:115], v[50:53]
	v_mfma_f32_16x16x32_bf16 v[38:41], v[100:103], v[108:111], v[38:41]
	s_waitcnt vmcnt(8)
	v_mfma_f32_16x16x32_bf16 v[6:9], v[100:103], v[116:119], v[6:9]
	v_mfma_f32_16x16x32_bf16 v[42:45], v[96:99], v[116:119], v[42:45]
	s_waitcnt vmcnt(6)
; #define LAS __attribute__((address_space(3)))
;     __device__ __forceinline__ void prep_commit(LAS unsigned char* lds, const PrepRegs& r, int ui, int tid) const { rs_commit(lds, r, ui, tid); }
;     __device__ __forceinline__ void prep_commit(LAS unsigned char* lds, const PrepRegs& r, int ui, int tid) const { rs_commit(lds, r, ui, tid); }
; __device__ __forceinline__ void rs_commit(LAS unsigned char* lds, const PrepRegs& r, int ui, int tid) {
;     const f32x4 s4 = r.a + r.b; float s = (s4[0] + s4[1]) + (s4[2] + s4[3]); s += __shfl_xor(s, 1);
;     if ((tid & 1) == 0) ((LAS float*)(lds + LDS_RSTAB))[(ui & 1) * 256 + (tid >> 1)] = rsqrtf(s * (1.0f / DM) + EPS);
; }
; template <class Epi, int K>
; __device__ __forceinline__ void gemm_tail(LAS unsigned char* lds, const bf16_t* A, const bf16_t* Bt, const int N, const Epi& E, const int bid, const int G, const int tid_in) {
;     ...
;             for (int s = 0; s < 4; ++s) if (sb + s < NS) {
; #pragma unroll
;                 for (int bj = 0; bj < 2; ++bj)
; #pragma unroll
;                     for (int m = 0; m < 4; ++m)
; #pragma unroll
;                         for (int n = 0; n < 2; ++n) acc[bj][m][n] = __builtin_amdgcn_mfma_f32_16x16x32_bf16(bf[s][bj][n], af[s][m], acc[bj][m][n], 0, 0, 0);
;             }
;         }
;         E.prep_commit(lds, prt, 0, tid);
;         LAS f32x4* P = (LAS f32x4*)lds;
; #pragma unroll
;         for (int bj = 0; bj < 2; ++bj)
; #pragma unroll
;             for (int m = 0; m < 4; ++m)
; #pragma unroll
;                 for (int n = 0; n < 2; ++n) P[(wid * 16 + bj * 8 + m * 2 + n) * 64 + lane] = acc[bj][m][n];
;         __syncthreads();
	v_mfma_f32_16x16x32_bf16 v[14:17], v[124:127], v[104:107], v[14:17]
	v_mfma_f32_16x16x32_bf16 v[232:235], v[120:123], v[112:115], v[66:69]
	v_mfma_f32_16x16x32_bf16 v[202:205], v[124:127], v[112:115], v[18:21]
	v_mfma_f32_16x16x32_bf16 v[236:239], v[120:123], v[108:111], v[70:73]
	v_mfma_f32_16x16x32_bf16 v[26:29], v[124:127], v[108:111], v[26:29]
	v_mfma_f32_16x16x32_bf16 v[224:227], v[120:123], v[116:119], v[58:61]
	s_nop 2
	v_mfma_f32_16x16x32_bf16 v[186:189], v[124:127], v[116:119], v[34:37]
	s_nop 2
	s_waitcnt vmcnt(4)
	v_mfma_f32_16x16x32_bf16 v[70:73], v[128:131], v[132:135], v[22:25]
	s_waitcnt vmcnt(3)
	v_mfma_f32_16x16x32_bf16 v[66:69], v[136:139], v[132:135], v[46:49]
	s_nop 2
	v_mfma_f32_16x16x32_bf16 v[22:25], v[128:131], v[248:251], v[38:41]
	s_nop 2
	s_waitcnt vmcnt(2)
	v_mfma_f32_16x16x32_bf16 v[50:53], v[136:139], v[140:143], v[50:53]
	v_mfma_f32_16x16x32_bf16 v[18:21], v[136:139], v[248:251], v[228:231]
	s_waitcnt vmcnt(1)
	v_mfma_f32_16x16x32_bf16 v[2:5], v[136:139], v[144:147], v[42:45]
	s_nop 2
	v_mfma_f32_16x16x32_bf16 v[62:65], v[120:123], v[104:107], v[62:65]
	global_load_dwordx4 v[10:13], v[10:11], off offset:192
	s_waitcnt vmcnt(1)
	v_mfma_f32_16x16x32_bf16 v[74:77], v[148:151], v[132:135], v[62:65]
	s_waitcnt vmcnt(0)
	v_mfma_f32_16x16x32_bf16 v[78:81], v[10:13], v[132:135], v[14:17]
	global_load_dwordx4 v[34:37], v[176:177], off offset:16
	s_nop 1
	global_load_dwordx4 v[14:17], v[176:177], off
	v_mfma_f32_16x16x32_bf16 v[54:57], v[128:131], v[140:143], v[30:33]
	s_waitcnt vmcnt(0)
	v_pk_add_f32 v[36:37], v[16:17], v[36:37]
	v_pk_add_f32 v[34:35], v[14:15], v[34:35]
	v_mfma_f32_16x16x32_bf16 v[6:9], v[128:131], v[144:147], v[6:9]
	v_add_f32_e32 v0, v34, v35
	v_add_f32_e32 v34, v36, v37
	v_add_f32_e32 v0, v0, v34
	ds_bpermute_b32 v34, v208, v0
	v_mfma_f32_16x16x32_bf16 v[62:65], v[148:151], v[140:143], v[232:235]
	v_mfma_f32_16x16x32_bf16 v[58:61], v[10:13], v[140:143], v[202:205]
	v_mfma_f32_16x16x32_bf16 v[30:33], v[148:151], v[248:251], v[236:239]
	v_mfma_f32_16x16x32_bf16 v[26:29], v[10:13], v[248:251], v[26:29]
	v_mfma_f32_16x16x32_bf16 v[14:17], v[148:151], v[144:147], v[224:227]
	v_mfma_f32_16x16x32_bf16 v[10:13], v[10:13], v[144:147], v[186:189]
	s_and_saveexec_b64 s[14:15], s[36:37]
	s_cbranch_execz .LBB0_324
	s_waitcnt lgkmcnt(0)
	v_add_f32_e32 v0, v0, v34
	v_fmamk_f32 v0, v0, 0x3a800000, v214
	s_mov_b32 s11, 0x800000
	v_mul_f32_e32 v34, 0x4b800000, v0
	v_cmp_gt_f32_e32 vcc, s11, v0
	s_nop 1
	v_cndmask_b32_e32 v0, v0, v34, vcc
	v_rsq_f32_e32 v0, v0
	s_nop 0
	v_mul_f32_e32 v34, 0x45800000, v0
	v_cndmask_b32_e32 v0, v0, v34, vcc
	ds_write_b32 v209, v0
.LBB0_324:
	s_or_b64 exec, exec, s[14:15]
	v_add_u32_e32 v0, s2, v210
	s_andn2_b64 vcc, exec, s[8:9]
	s_cbranch_vccz .Lp1t_nopw
	ds_write_b128 v0, v[70:73]
	ds_write_b128 v0, v[66:69] offset:1024
	ds_write_b128 v0, v[54:57] offset:2048
	ds_write_b128 v0, v[50:53] offset:3072
	ds_write_b128 v0, v[22:25] offset:4096
	ds_write_b128 v0, v[18:21] offset:5120
	ds_write_b128 v0, v[6:9] offset:6144
	ds_write_b128 v0, v[2:5] offset:7168
	ds_write_b128 v0, v[74:77] offset:8192
	ds_write_b128 v0, v[78:81] offset:9216
	ds_write_b128 v0, v[62:65] offset:10240
	ds_write_b128 v0, v[58:61] offset:11264
	ds_write_b128 v0, v[30:33] offset:12288
	ds_write_b128 v0, v[26:29] offset:13312
	ds_write_b128 v0, v[14:17] offset:14336
	ds_write_b128 v0, v[10:13] offset:15360
.Lp1t_nopw:
	s_waitcnt lgkmcnt(0)
	s_barrier
	s_cbranch_vccnz .LBB0_321
	s_movk_i32 s11, 0x4000
;     __device__ __forceinline__ void run(const f32x4 (&acc)[2][2][4][2], const Unit& u, int wr, int wc, int fr, int fq, const int nai, LAS unsigned char* lds, const int ui) const {
;     ...
;         const int pn = u.pn; const bool isqk = pn < 4;
;         f32x4 gv[2][2];
; #pragma unroll
;         for (int bj = 0; bj < 2; ++bj)
; #pragma unroll
;             for (int n = 0; n < 2; ++n) gv[bj][n] = isqk ? *(const f32x4*)((pn < 2 ? gq : gk) + 32 * bj + 8 * fq + 4 * n) : (f32x4){1.f, 1.f, 1.f, 1.f};
;         const float qs = (pn < 2) ? C2 : 1.f;
; template <class Epi, int K>
; __device__ __forceinline__ void gemm_tail(LAS unsigned char* lds, const bf16_t* A, const bf16_t* Bt, const int N, const Epi& E, const int bid, const int G, const int tid_in) {
;     ...
;             for (int w = 1; w < 8; ++w) {
; #pragma unroll
;                 for (int bj = 0; bj < 2; ++bj)
; #pragma unroll
;                     for (int m = 0; m < 4; ++m)
; #pragma unroll
;                         for (int n = 0; n < 2; ++n) full[0][bj][m][n] += P[(w * 16 + bj * 8 + m * 2 + n) * 64 + lane];
;                 asm volatile("" ::: "memory");
;             }
;             Unit u; u.pm = MMAIN / 256; u.pn = pn;
;             E.run(full, u, 0, wc, lane & 15, lane >> 4, 1, lds, 0);
.LBB0_326:
	v_add_u32_e32 v0, s11, v210
	s_addk_i32 s11, 0x4000
	s_cmp_lg_u32 s11, 0x20000
	ds_read_b128 v[34:37], v0
	ds_read_b128 v[38:41], v0 offset:1024
	ds_read_b128 v[42:45], v0 offset:2048
	ds_read_b128 v[46:49], v0 offset:3072
	ds_read_b128 v[186:189], v0 offset:4096
	ds_read_b128 v[202:205], v0 offset:5120
	ds_read_b128 v[224:227], v0 offset:6144
	ds_read_b128 v[228:231], v0 offset:7168
	s_waitcnt lgkmcnt(7)
	v_pk_add_f32 v[72:73], v[72:73], v[36:37]
	v_pk_add_f32 v[70:71], v[70:71], v[34:35]
	ds_read_b128 v[34:37], v0 offset:8192
	s_waitcnt lgkmcnt(7)
	v_pk_add_f32 v[68:69], v[68:69], v[40:41]
	v_pk_add_f32 v[66:67], v[66:67], v[38:39]
	ds_read_b128 v[38:41], v0 offset:9216
	s_waitcnt lgkmcnt(7)
	v_pk_add_f32 v[56:57], v[56:57], v[44:45]
	v_pk_add_f32 v[54:55], v[54:55], v[42:43]
	ds_read_b128 v[42:45], v0 offset:10240
	s_waitcnt lgkmcnt(7)
	v_pk_add_f32 v[52:53], v[52:53], v[48:49]
	v_pk_add_f32 v[50:51], v[50:51], v[46:47]
	ds_read_b128 v[46:49], v0 offset:11264
	s_waitcnt lgkmcnt(7)
	v_pk_add_f32 v[24:25], v[24:25], v[188:189]
	v_pk_add_f32 v[22:23], v[22:23], v[186:187]
	ds_read_b128 v[186:189], v0 offset:12288
	s_waitcnt lgkmcnt(7)
	v_pk_add_f32 v[20:21], v[20:21], v[204:205]
	v_pk_add_f32 v[18:19], v[18:19], v[202:203]
	ds_read_b128 v[202:205], v0 offset:13312
	s_waitcnt lgkmcnt(7)
	v_pk_add_f32 v[8:9], v[8:9], v[226:227]
	v_pk_add_f32 v[6:7], v[6:7], v[224:225]
	ds_read_b128 v[224:227], v0 offset:14336
	s_waitcnt lgkmcnt(7)
	v_pk_add_f32 v[4:5], v[4:5], v[230:231]
	v_pk_add_f32 v[2:3], v[2:3], v[228:229]
	ds_read_b128 v[228:231], v0 offset:15360
	s_waitcnt lgkmcnt(7)
	v_pk_add_f32 v[76:77], v[76:77], v[36:37]
	v_pk_add_f32 v[74:75], v[74:75], v[34:35]
	s_waitcnt lgkmcnt(6)
	v_pk_add_f32 v[80:81], v[80:81], v[40:41]
	v_pk_add_f32 v[78:79], v[78:79], v[38:39]
	s_waitcnt lgkmcnt(5)
	v_pk_add_f32 v[64:65], v[64:65], v[44:45]
	v_pk_add_f32 v[62:63], v[62:63], v[42:43]
	s_waitcnt lgkmcnt(4)
	v_pk_add_f32 v[60:61], v[60:61], v[48:49]
	v_pk_add_f32 v[58:59], v[58:59], v[46:47]
	s_waitcnt lgkmcnt(3)
	v_pk_add_f32 v[32:33], v[32:33], v[188:189]
	v_pk_add_f32 v[30:31], v[30:31], v[186:187]
	s_waitcnt lgkmcnt(2)
	v_pk_add_f32 v[28:29], v[28:29], v[204:205]
	v_pk_add_f32 v[26:27], v[26:27], v[202:203]
	s_waitcnt lgkmcnt(1)
	v_pk_add_f32 v[16:17], v[16:17], v[226:227]
	v_pk_add_f32 v[14:15], v[14:15], v[224:225]
	s_waitcnt lgkmcnt(0)
	v_pk_add_f32 v[12:13], v[12:13], v[230:231]
	v_pk_add_f32 v[10:11], v[10:11], v[228:229]
	s_cbranch_scc1 .LBB0_326
	ds_read_b128 v[88:91], v210
	ds_read_b128 v[92:95], v210 offset:1024
	ds_read_b128 v[96:99], v210 offset:2048
	ds_read_b128 v[100:103], v210 offset:3072
	ds_read_b128 v[104:107], v210 offset:4096
	ds_read_b128 v[108:111], v210 offset:5120
	ds_read_b128 v[112:115], v210 offset:6144
	ds_read_b128 v[116:119], v210 offset:7168
	ds_read_b128 v[120:123], v210 offset:8192
	ds_read_b128 v[124:127], v210 offset:9216
	ds_read_b128 v[128:131], v210 offset:10240
	ds_read_b128 v[132:135], v210 offset:11264
	ds_read_b128 v[136:139], v210 offset:12288
	ds_read_b128 v[140:143], v210 offset:13312
	ds_read_b128 v[144:147], v210 offset:14336
	ds_read_b128 v[148:151], v210 offset:15360
	s_waitcnt lgkmcnt(0)
	s_cmp_lt_i32 s6, 4
	s_cselect_b64 s[14:15], -1, 0
	s_cmp_lt_i32 s6, 2
	v_mov_b32_e32 v42, 1.0
	s_cselect_b64 s[40:41], -1, 0
	s_cmp_gt_i32 s6, 3
	v_lshlrev_b32_e32 v0, 2, v82
	v_mov_b32_e32 v46, 1.0
	v_mov_b32_e32 v47, v42
	v_mov_b32_e32 v48, 1.0
	v_mov_b32_e32 v49, 1.0
	s_cbranch_scc1 .LBB0_329
	s_and_b64 s[20:21], s[40:41], exec
	s_cselect_b32 s21, s59, s61
	s_cselect_b32 s20, s58, s60
	global_load_dwordx4 v[46:49], v0, s[20:21]
